# attention tile loop: uniform tile bases in SGPRs (one lane offset for 8 loads), packed P-m subtract and row-sum tree
# speedup vs baseline: 1.0012x; 1.0012x over previous
; #define LAS __attribute__((address_space(3)))
; __device__ __forceinline__ void attn_mfma_item(const bf16* u, bf16* y, const float* cl, const float* tot, LAS unsigned char* wl, int item, int lane) {
;     ...
;     f32x16 O0, O1;
; #pragma unroll
;     for (int i = 0; i < 16; ++i) { O0[i] = 0.f; O1[i] = 0.f; }
;     float mrun = -1e30f, lsum = 0.f, Rsb = 1.f, Doff = 0.f;
;     const float clt = fox ? clh[t] : 0.f;
;     LAS float* gl = (LAS float*)(wl + 4608);
;     const int trbase = (4 * hi + ((lane >> 2) & 3)) * PV64 + (16 * ((lane >> 4) & 1) + 4 * (lane & 3)) * 2;
;     const unsigned lane_off = (unsigned)((lane >> 3) * NU + 8 * (lane & 7)) * 2u;
;     v4u kn[4], vn[4]; float gn = 0.f;
;     { const char* tb = ubc + (size_t)(qb * 32) * NU * 2;
; #pragma unroll
;       for (int i = 0; i < 4; ++i) { kn[i] = *(const v4u*)(tb + (size_t)(8 * i * NU + koff) * 2 + lane_off); vn[i] = *(const v4u*)(tb + (size_t)(8 * i * NU + voff) * 2 + lane_off); }
;       if (fox) gn = clh[qb * 32 + r]; }
;     LAS unsigned char* kl = wl + 4736;
;     const int kfoff = r * PV64 + 16 * hi;
;     const float SC2 = 0.125f * 1.4426950408889634f;
;     { LAS unsigned char* z = wl + 9344 + (lane >> 3) * PV64 + 16 * (lane & 7);
; #pragma unroll
;       for (int i = 0; i < 4; ++i) *(LAS v4u*)(z + 8 * i * PV64) = (v4u){0u, 0u, 0u, 0u}; }
;     s16x8 Pp0 = {0, 0, 0, 0, 0, 0, 0, 0}, Pp1 = {0, 0, 0, 0, 0, 0, 0, 0};
;     int vlast = 0;
.LBB0_747:
	s_mov_b32 s84, s85
	s_mov_b32 s86, s85
	s_mov_b32 s87, s85
	v_mov_b64_e32 v[4:5], s[84:85]
	v_mov_b64_e32 v[6:7], s[86:87]
	s_cmpk_gt_i32 s33, 0x13ff
	ds_write_b128 v207, v[4:7] offset:9344
	ds_write_b128 v207, v[4:7] offset:10496
	ds_write_b128 v207, v[4:7] offset:11648
	ds_write_b128 v207, v[4:7] offset:12800
	s_cbranch_scc1 .LBB0_775
	s_waitcnt vmcnt(8)
	v_mov_b32_e32 v16, v3
	v_mov_b32_e32 v17, v3
	v_mov_b32_e32 v2, v3
	v_mov_b32_e32 v4, v3
	v_mov_b32_e32 v5, v3
	v_mov_b32_e32 v6, v3
	v_mov_b32_e32 v7, v3
	v_mov_b32_e32 v8, v3
	v_mov_b32_e32 v9, v3
	v_mov_b32_e32 v10, v3
	v_mov_b32_e32 v11, v3
	v_mov_b32_e32 v12, v3
	v_mov_b32_e32 v13, v3
	v_mov_b32_e32 v14, v3
	v_mov_b32_e32 v15, v3
	v_mov_b64_e32 v[34:35], v[16:17]
	v_mov_b32_e32 v52, 0
	v_mov_b64_e32 v[32:33], v[14:15]
	v_mov_b64_e32 v[30:31], v[12:13]
	v_mov_b64_e32 v[28:29], v[10:11]
	v_mov_b64_e32 v[26:27], v[8:9]
	v_mov_b64_e32 v[24:25], v[6:7]
	v_mov_b64_e32 v[22:23], v[4:5]
	v_mov_b64_e32 v[20:21], v[2:3]
	v_mov_b64_e32 v[18:19], v[16:17]
	s_lshl_b32 s84, s94, 3
	v_lshl_add_u64 v[122:123], s[70:71], 0, v[150:151]
	s_add_u32 s54, s54, s70
	s_addc_u32 s55, s55, s71
	s_add_u32 s56, s56, s70
	s_addc_u32 s57, s57, s71
	s_add_u32 s58, s58, s70
	s_addc_u32 s59, s59, s71
	s_add_u32 s60, s60, s70
	s_addc_u32 s61, s61, s71
	s_add_u32 s62, s62, s70
	s_addc_u32 s63, s63, s71
	s_add_u32 s64, s64, s70
	s_addc_u32 s65, s65, s71
	s_add_u32 s66, s66, s70
	s_addc_u32 s67, s67, s71
	s_add_u32 s68, s68, s70
	s_addc_u32 s69, s69, s71
	s_sub_i32 s83, s73, 32
	s_mov_b32 s73, 0
	v_mov_b32_e32 v136, 1.0
	v_mov_b32_e32 v121, 0
	v_mov_b32_e32 v138, 0xf149f2ca
	v_mov_b64_e32 v[16:17], v[14:15]
	v_mov_b64_e32 v[14:15], v[12:13]
	v_mov_b64_e32 v[12:13], v[10:11]
	v_mov_b64_e32 v[10:11], v[8:9]
	v_mov_b64_e32 v[8:9], v[6:7]
	v_mov_b64_e32 v[6:7], v[4:5]
	v_mov_b64_e32 v[4:5], v[2:3]
	v_mov_b32_e32 v137, 0
	v_mov_b32_e32 v53, v52
	v_mov_b32_e32 v54, v52
	v_mov_b32_e32 v55, v52
	v_mov_b32_e32 v116, v52
	v_mov_b32_e32 v117, v52
	v_mov_b32_e32 v118, v52
	v_mov_b32_e32 v119, v52
	s_branch .LBB0_750

; #define LAS __attribute__((address_space(3)))
; __device__ __forceinline__ s16x4 tr_read(LAS const unsigned char* p) { return __builtin_bit_cast(s16x4, __builtin_amdgcn_ds_read_tr16_b64_v4i16((LAS s16x4*)p)); }
; __device__ __forceinline__ s16x8 cat8(s16x4 a, s16x4 b) { return (s16x8){a[0], a[1], a[2], a[3], b[0], b[1], b[2], b[3]}; }
; #define MFMA32(a, b, c) __builtin_amdgcn_mfma_f32_32x32x16_bf16(a, b, c, 0, 0, 0)
; __device__ __forceinline__ void attn_mfma_item(const bf16* u, bf16* y, const float* cl, const float* tot, LAS unsigned char* wl, int item, int lane) {
;     ...
;         if (jt > 0) { const char* tb = ubc + (size_t)((jt - 1) * 32) * NU * 2;
; #pragma unroll
;           for (int i = 0; i < 4; ++i) { kn[i] = *(const v4u*)(tb + (size_t)(8 * i * NU + koff) * 2 + lane_off); vn[i] = *(const v4u*)(tb + (size_t)(8 * i * NU + voff) * 2 + lane_off); }
;           if (fox) gn = clh[(jt - 1) * 32 + r]; }
;         s16x8 Kf[4];
; #pragma unroll
;         for (int d0 = 0; d0 < 4; ++d0) Kf[d0] = *(LAS const s16x8*)(kl + kfoff + 32 * d0);
;         LAS const unsigned char* vb = wl + vprev + trbase;
;         const s16x8 V00 = cat8(tr_read(vb), tr_read(vb + 8 * PV64)), V01 = cat8(tr_read(vb + 16 * PV64), tr_read(vb + 24 * PV64));
;         const s16x8 V10 = cat8(tr_read(vb + 64), tr_read(vb + 8 * PV64 + 64)), V11 = cat8(tr_read(vb + 16 * PV64 + 64), tr_read(vb + 24 * PV64 + 64));
;         f32x16 Sx;
; #pragma unroll
;         for (int i = 0; i < 16; ++i) Sx[i] = 0.f;
;         Sx = MFMA32(Kf[0], Qf[0], Sx); O0 = MFMA32(V00, Pp0, O0);
;         Sx = MFMA32(Kf[1], Qf[1], Sx); O1 = MFMA32(V10, Pp0, O1);
;         Sx = MFMA32(Kf[2], Qf[2], Sx); O0 = MFMA32(V01, Pp1, O0);
;         Sx = MFMA32(Kf[3], Qf[3], Sx); O1 = MFMA32(V11, Pp1, O1);
.LBB0_752:
	s_cmp_lg_u32 s1, 0
	s_cselect_b64 s[86:87], -1, 0
	s_cmp_eq_u32 s1, 0
	s_cbranch_scc1 .LBB0_755
	v_mad_u32_u24 v226, s83, v215, v150
	s_nop 0
	global_load_dwordx4 v[84:87], v226, s[54:55]
	global_load_dwordx4 v[88:91], v226, s[56:57]
	global_load_dwordx4 v[92:95], v226, s[58:59]
	global_load_dwordx4 v[96:99], v226, s[60:61]
	global_load_dwordx4 v[100:103], v226, s[62:63]
	global_load_dwordx4 v[104:107], v226, s[64:65]
	global_load_dwordx4 v[108:111], v226, s[66:67]
	global_load_dwordx4 v[112:115], v226, s[68:69]
	s_and_b64 vcc, exec, s[92:93]
	s_cbranch_vccnz .LBB0_755
	v_add_lshl_u32 v227, s83, v145, 2
	s_nop 0
	global_load_dword v135, v227, s[52:53]
.LBB0_755:
	v_add_u32_e32 v1, v190, v187
	ds_read_b128 v[36:39], v1 offset:4736
	ds_read_b128 v[56:59], v1 offset:4768
	v_subrev_u32_e32 v2, s33, v189
	ds_read_b64_tr_b16 v[60:61], v2 offset:9344
	ds_read_b64_tr_b16 v[62:63], v2 offset:10496
	ds_read_b64_tr_b16 v[66:67], v2 offset:10560
	ds_read_b64_tr_b16 v[64:65], v2 offset:9408
	s_waitcnt lgkmcnt(2)
	v_mfma_f32_32x32x16_bf16 v[20:35], v[60:63], v[52:55], v[20:35]
	s_cmp_eq_u32 s73, 0
	s_cselect_b64 s[94:95], -1, 0
	s_mov_b64 s[70:71], -1
	s_and_b64 vcc, exec, s[50:51]
	v_mfma_f32_32x32x16_bf16 v[36:51], v[36:39], v[68:71], 0
	v_mfma_f32_32x32x16_bf16 v[36:51], v[56:59], v[72:75], v[36:51]
	s_waitcnt lgkmcnt(0)
	v_mfma_f32_32x32x16_bf16 v[4:19], v[64:67], v[52:55], v[4:19]
	ds_read_b128 v[52:55], v1 offset:4800
	ds_read_b128 v[56:59], v1 offset:4832
	s_andn2_b64 s[94:95], exec, s[94:95]
	s_waitcnt lgkmcnt(1)
	v_mfma_f32_32x32x16_bf16 v[36:51], v[52:55], v[76:79], v[36:51]
	ds_read_b64_tr_b16 v[52:53], v2 offset:11648
	ds_read_b64_tr_b16 v[54:55], v2 offset:12800
	ds_read_b64_tr_b16 v[126:127], v2 offset:12864
	ds_read_b64_tr_b16 v[124:125], v2 offset:11712
	s_waitcnt lgkmcnt(2)
	v_mfma_f32_32x32x16_bf16 v[20:35], v[52:55], v[116:119], v[20:35]
	v_mfma_f32_32x32x16_bf16 v[36:51], v[56:59], v[80:83], v[36:51]
	s_waitcnt lgkmcnt(0)
	v_mfma_f32_32x32x16_bf16 v[4:19], v[124:127], v[116:119], v[4:19]
	s_cbranch_vccz .LBB0_759
	s_nop 8
	v_exp_f32_e32 v1, v36
	v_exp_f32_e32 v2, v37
	v_exp_f32_e32 v52, v38
	v_exp_f32_e32 v53, v51
	v_add_f32_e32 v1, 1.0, v1
	v_add_f32_e32 v2, 1.0, v2
	v_rcp_f32_e32 v116, v1
	v_rcp_f32_e32 v117, v2
	v_exp_f32_e32 v1, v39
	v_add_f32_e32 v2, 1.0, v52
	v_rcp_f32_e32 v118, v2
	v_exp_f32_e32 v2, v40
	v_add_f32_e32 v1, 1.0, v1
	v_rcp_f32_e32 v119, v1
	v_exp_f32_e32 v1, v41
	v_add_f32_e32 v2, 1.0, v2
	v_rcp_f32_e32 v66, v2
	v_exp_f32_e32 v2, v42
	v_add_f32_e32 v1, 1.0, v1
	v_rcp_f32_e32 v67, v1
	v_exp_f32_e32 v1, v43
	v_add_f32_e32 v2, 1.0, v2
	v_rcp_f32_e32 v124, v2
	v_exp_f32_e32 v2, v44
	v_add_f32_e32 v1, 1.0, v1
	v_rcp_f32_e32 v125, v1
	v_exp_f32_e32 v1, v45
	v_add_f32_e32 v2, 1.0, v2
	v_rcp_f32_e32 v126, v2
	v_exp_f32_e32 v2, v46
	v_exp_f32_e32 v52, v47
	v_add_f32_e32 v1, 1.0, v1
	v_rcp_f32_e32 v127, v1
	v_add_f32_e32 v1, 1.0, v2
	v_rcp_f32_e32 v132, v1
	v_add_f32_e32 v1, 1.0, v52
	v_rcp_f32_e32 v133, v1
	v_exp_f32_e32 v1, v48
	v_exp_f32_e32 v2, v49
	v_exp_f32_e32 v52, v50
	v_add_f32_e32 v53, 1.0, v53
	v_add_f32_e32 v1, 1.0, v1
	v_add_f32_e32 v2, 1.0, v2
	v_add_f32_e32 v52, 1.0, v52
	v_rcp_f32_e32 v131, v53
	v_rcp_f32_e32 v130, v52
	v_rcp_f32_e32 v129, v2
	v_rcp_f32_e32 v128, v1
	v_sub_f32_e32 v63, 1.0, v131
	v_sub_f32_e32 v56, 1.0, v130
	v_sub_f32_e32 v61, 1.0, v129
	v_sub_f32_e32 v58, 1.0, v128
	v_sub_f32_e32 v59, 1.0, v133
	v_sub_f32_e32 v54, 1.0, v132
	v_sub_f32_e32 v57, 1.0, v127
	v_sub_f32_e32 v60, 1.0, v126
	v_sub_f32_e32 v55, 1.0, v125
	v_sub_f32_e32 v52, 1.0, v124
	v_sub_f32_e32 v65, 1.0, v67
	v_sub_f32_e32 v62, 1.0, v66
	v_sub_f32_e32 v53, 1.0, v119
	v_sub_f32_e32 v2, 1.0, v118
	s_and_b64 vcc, exec, s[94:95]
	v_sub_f32_e32 v1, 1.0, v117
	v_sub_f32_e32 v64, 1.0, v116
	s_cbranch_vccnz .LBB0_758
	v_readlane_b32 s34, v254, 28
	v_readlane_b32 s70, v254, 0
	v_readlane_b32 s96, v254, 2
	v_readlane_b32 s48, v254, 4
	v_readlane_b32 s90, v254, 6
	v_readlane_b32 s88, v254, 8
	v_readlane_b32 s80, v254, 10
	v_readlane_b32 s16, v254, 12
	v_readlane_b32 s76, v254, 14
	v_readlane_b32 s78, v254, 16
	v_readlane_b32 s74, v254, 18
	v_readlane_b32 s42, v254, 20
	v_readlane_b32 s40, v254, 22
	v_readlane_b32 s38, v254, 24
	v_readlane_b32 s36, v254, 26
	v_readlane_b32 s35, v254, 29
	v_readlane_b32 s71, v254, 1
	v_readlane_b32 s97, v254, 3
	v_readlane_b32 s49, v254, 5
	v_readlane_b32 s91, v254, 7
	v_readlane_b32 s89, v254, 9
	v_readlane_b32 s81, v254, 11
	v_readlane_b32 s17, v254, 13
	v_readlane_b32 s77, v254, 15
	v_readlane_b32 s79, v254, 17
	v_readlane_b32 s75, v254, 19
	v_readlane_b32 s43, v254, 21
	v_readlane_b32 s41, v254, 23
	v_readlane_b32 s39, v254, 25
	v_readlane_b32 s37, v254, 27
	s_or_b64 vcc, s[34:35], s[18:19]
	v_cndmask_b32_e64 v63, 1.0, v63, s[70:71]
	v_cndmask_b32_e64 v56, 1.0, v56, s[96:97]
	v_cndmask_b32_e64 v61, 1.0, v61, s[48:49]
	v_cndmask_b32_e64 v58, 1.0, v58, s[90:91]
	v_cndmask_b32_e64 v59, 1.0, v59, s[88:89]
	v_cndmask_b32_e64 v54, 1.0, v54, s[80:81]
	v_cndmask_b32_e64 v57, 1.0, v57, s[16:17]
	v_cndmask_b32_e64 v60, 1.0, v60, s[76:77]
	v_cndmask_b32_e64 v55, 1.0, v55, s[78:79]
	v_cndmask_b32_e64 v52, 1.0, v52, s[74:75]
	v_cndmask_b32_e64 v65, 1.0, v65, s[42:43]
	v_cndmask_b32_e64 v62, 1.0, v62, s[40:41]
	v_cndmask_b32_e64 v53, 1.0, v53, s[38:39]
	v_cndmask_b32_e64 v2, 1.0, v2, s[36:37]
	v_cndmask_b32_e64 v1, 1.0, v1, s[34:35]
	v_cndmask_b32_e32 v64, 1.0, v64, vcc
	v_cndmask_b32_e64 v131, 0, v131, s[70:71]
	v_cndmask_b32_e64 v130, 0, v130, s[96:97]
	v_cndmask_b32_e64 v129, 0, v129, s[48:49]
	v_cndmask_b32_e64 v128, 0, v128, s[90:91]
	v_cndmask_b32_e64 v133, 0, v133, s[88:89]
	v_cndmask_b32_e64 v132, 0, v132, s[80:81]
	v_cndmask_b32_e64 v127, 0, v127, s[16:17]
	v_cndmask_b32_e64 v126, 0, v126, s[76:77]
	v_cndmask_b32_e64 v125, 0, v125, s[78:79]
	v_cndmask_b32_e64 v124, 0, v124, s[74:75]
	v_cndmask_b32_e64 v67, 0, v67, s[42:43]
	v_cndmask_b32_e64 v66, 0, v66, s[40:41]
	v_cndmask_b32_e64 v119, 0, v119, s[38:39]
	v_cndmask_b32_e64 v118, 0, v118, s[36:37]
	v_cndmask_b32_e64 v117, 0, v117, s[34:35]
	v_cndmask_b32_e32 v116, 0, v116, vcc

; __device__ __forceinline__ void attn_mfma_item(const bf16* u, bf16* y, const float* cl, const float* tot, LAS unsigned char* wl, int item, int lane) {
;     ...
;             const float msh = mrun - off; float ps = 0.f;
; #pragma unroll
;             for (int i = 0; i < 16; ++i) { P[i] = __builtin_amdgcn_exp2f(P[i] - msh); ps += P[i]; }
;             lsum += ps;
.LBB0_767:
	v_sub_f32_e32 v2, v138, v1
	s_nop 0
	v_pk_add_f32 v[36:37], v[36:37], v[2:3] op_sel_hi:[1,0] neg_lo:[0,1] neg_hi:[0,1]
	v_pk_add_f32 v[54:55], v[54:55], v[2:3] op_sel_hi:[1,0] neg_lo:[0,1] neg_hi:[0,1]
	v_pk_add_f32 v[40:41], v[40:41], v[2:3] op_sel_hi:[1,0] neg_lo:[0,1] neg_hi:[0,1]
	v_pk_add_f32 v[42:43], v[42:43], v[2:3] op_sel_hi:[1,0] neg_lo:[0,1] neg_hi:[0,1]
	v_pk_add_f32 v[44:45], v[44:45], v[2:3] op_sel_hi:[1,0] neg_lo:[0,1] neg_hi:[0,1]
	v_pk_add_f32 v[46:47], v[46:47], v[2:3] op_sel_hi:[1,0] neg_lo:[0,1] neg_hi:[0,1]
	v_pk_add_f32 v[38:39], v[38:39], v[2:3] op_sel_hi:[1,0] neg_lo:[0,1] neg_hi:[0,1]
	v_pk_add_f32 v[50:51], v[50:51], v[2:3] op_sel_hi:[1,0] neg_lo:[0,1] neg_hi:[0,1]
	v_exp_f32_e32 v52, v36
	v_exp_f32_e32 v53, v37
	v_exp_f32_e32 v54, v54
	v_exp_f32_e32 v55, v55
	v_exp_f32_e32 v56, v40
	v_exp_f32_e32 v57, v41
	v_exp_f32_e32 v58, v42
	v_exp_f32_e32 v59, v43
	v_pk_add_f32 v[228:229], v[52:53], v[54:55]
	v_exp_f32_e32 v60, v44
	v_exp_f32_e32 v61, v45
	v_exp_f32_e32 v62, v46
	v_exp_f32_e32 v63, v47
	v_pk_add_f32 v[230:231], v[56:57], v[58:59]
	v_exp_f32_e32 v64, v38
	v_exp_f32_e32 v65, v39
	v_exp_f32_e32 v66, v50
	v_exp_f32_e32 v67, v51
	v_pk_add_f32 v[232:233], v[60:61], v[62:63]
	v_pk_add_f32 v[228:229], v[228:229], v[230:231]
	v_pk_add_f32 v[234:235], v[64:65], v[66:67]
	s_nop 0
	v_pk_add_f32 v[232:233], v[232:233], v[234:235]
	s_nop 0
	v_pk_add_f32 v[228:229], v[228:229], v[232:233]
	s_nop 0
	v_add_f32_e32 v1, v228, v229
	v_add_f32_e32 v121, v121, v1
	s_branch .LBB0_769
